# FoX tstart cumb loads issued together (3 round trips -> 1) on top of parallel list build and previous stack
# speedup vs baseline: 1.0141x; 1.0027x over previous
; DI void load_q(bf16x8 (&q)[8], const bf16* qrow, int h, const float* gain, int lane) {
;     float ss = 0.f;
; #pragma unroll
;     for (int s = 0; s < 8; ++s) { const u32x4 raw = *(const u32x4*)(qrow + 16 * s + 8 * h);
; #pragma unroll
;         for (int j = 0; j < 4; ++j) { const float a = __builtin_bit_cast(float, raw[j] << 16), b = __builtin_bit_cast(float, raw[j] & 0xffff0000u); ss += a * a + b * b; } }
; __global__ void __launch_bounds__(NTHR, 2) hybrid_fwd(P p) {
;     ...
;             for (;;) {
;                 if (tid == 0) *qslot = atomicAdd(qctr, 1u);
;                 __syncthreads();
;                 const int v = (int)*qslot;
;                 __syncthreads();
;                 if (v >= 1024) break;
;                 if (v < 512) { const int gg = v < 256 ? 1 : 0, idx = v & 255; if (PH(8)) nsa_unit(p, lds, (idx >> 1) * 4 + ((idx & 1) * 2 + gg), l, wv); }
;                 else { if (PH(7)) fox_unit(p, lds, v - 512, l, wv); }
.LBB0_522:
	s_or_b64 exec, exec, s[2:3]
	v_mov_b32_e32 v0, s29
	s_waitcnt lgkmcnt(0)
	s_barrier
	ds_read_b32 v0, v0
	s_movk_i32 s0, 0x3ff
	s_mov_b64 s[2:3], -1
	s_waitcnt lgkmcnt(0)
	s_barrier
	v_cmp_lt_i32_e32 vcc, s0, v0
	v_readfirstlane_b32 s30, v0
	s_cbranch_vccnz .LBB0_519
	s_cmpk_gt_i32 s30, 0x1ff
	s_cbranch_scc0 .LBB0_588
	s_add_i32 s0, s30, 0xfffffe00
	v_readlane_b32 s1, v252, 5
	v_mbcnt_lo_u32_b32 v114, -1, 0
	v_mbcnt_hi_u32_b32 v114, -1, v114
	s_lshr_b32 s0, s0, 4
	s_xor_b32 s6, s0, 31
	v_add_u32_e32 v33, s1, v114
	v_ashrrev_i32_e32 v0, 1, v33
	s_lshl_b32 s4, s6, 8
	v_and_b32_e32 v0, 0xffffffe0, v0
	v_and_b32_e32 v115, 31, v114
	s_bfe_u32 s7, s30, 0x10003
	s_and_b32 s0, s30, 7
	v_add_u32_e32 v0, s4, v0
	v_or_b32_e32 v196, v0, v115
	s_lshl_b32 s3, s0, 14
	s_lshl_b32 s1, s7, 13
	s_or_b32 s16, s3, s1
	v_ashrrev_i32_e32 v197, 31, v196
	v_lshl_add_u64 v[2:3], s[16:17], 0, v[196:197]
	v_readlane_b32 s8, v253, 10
	v_bfe_u32 v199, v114, 5, 1
	v_lshlrev_b64 v[2:3], 8, v[2:3]
	v_readlane_b32 s9, v253, 11
	v_lshlrev_b32_e32 v0, 4, v199
	v_and_b32_e32 v208, 63, v114
	v_lshl_add_u64 v[2:3], s[8:9], 0, v[2:3]
	v_lshl_add_u64 v[2:3], v[2:3], 0, v[0:1]
	global_load_dwordx4 v[4:7], v[2:3], off
	global_load_dwordx4 v[136:139], v[2:3], off offset:32
	global_load_dwordx4 v[140:143], v[2:3], off offset:64
	global_load_dwordx4 v[144:147], v[2:3], off offset:96
	global_load_dwordx4 v[148:151], v[2:3], off offset:128
	global_load_dwordx4 v[152:155], v[2:3], off offset:160
	global_load_dwordx4 v[156:159], v[2:3], off offset:192
	global_load_dwordx4 v[160:163], v[2:3], off offset:224
	v_readlane_b32 s8, v255, 9
	v_readlane_b32 s9, v255, 10
	v_lshlrev_b32_e32 v14, 2, v208
	v_xor_b32_e32 v197, 0x80, v14
	s_and_b32 s2, s30, 15
	s_lshl_b32 s14, s2, 15
	v_readlane_b32 s2, v254, 0
	s_add_u32 s2, s2, s14
	v_readlane_b32 s3, v254, 1
	s_mov_b32 s5, s17
	s_addc_u32 s3, s3, 0
	s_mov_b64 s[10:11], 0
	s_waitcnt vmcnt(7)
	v_lshlrev_b32_e32 v8, 16, v4
	v_and_b32_e32 v4, 0xffff0000, v4
	v_mul_f32_e32 v4, v4, v4
	v_fmac_f32_e32 v4, v8, v8
	v_lshlrev_b32_e32 v8, 16, v5
	v_and_b32_e32 v5, 0xffff0000, v5
	v_mul_f32_e32 v5, v5, v5
	v_fmac_f32_e32 v5, v8, v8
	v_add_f32_e32 v4, v4, v5
	v_lshlrev_b32_e32 v5, 16, v6
	v_and_b32_e32 v6, 0xffff0000, v6
	v_mul_f32_e32 v6, v6, v6
	v_fmac_f32_e32 v6, v5, v5
	v_add_f32_e32 v4, v6, v4
	v_and_b32_e32 v6, 0xffff0000, v7
	v_lshlrev_b32_e32 v5, 16, v7
	v_mul_f32_e32 v6, v6, v6
	v_fmac_f32_e32 v6, v5, v5
	v_add_f32_e32 v8, v6, v4
	s_waitcnt vmcnt(6)
	v_mov_b32_e32 v4, v136
	v_mov_b32_e32 v5, v137
	v_mov_b32_e32 v6, v138
	v_mov_b32_e32 v7, v139
	v_lshlrev_b32_e32 v9, 16, v4
	v_and_b32_e32 v4, 0xffff0000, v4
	v_mul_f32_e32 v4, v4, v4
	v_fmac_f32_e32 v4, v9, v9
	v_add_f32_e32 v4, v4, v8
	v_lshlrev_b32_e32 v8, 16, v5
	v_and_b32_e32 v5, 0xffff0000, v5
	v_mul_f32_e32 v5, v5, v5
	v_fmac_f32_e32 v5, v8, v8
	v_add_f32_e32 v4, v5, v4
	v_lshlrev_b32_e32 v5, 16, v6
	v_and_b32_e32 v6, 0xffff0000, v6
	v_mul_f32_e32 v6, v6, v6
	v_fmac_f32_e32 v6, v5, v5
	v_add_f32_e32 v4, v6, v4
	v_and_b32_e32 v6, 0xffff0000, v7
	v_lshlrev_b32_e32 v5, 16, v7
	v_mul_f32_e32 v6, v6, v6
	v_fmac_f32_e32 v6, v5, v5
	v_add_f32_e32 v8, v6, v4
	s_waitcnt vmcnt(5)
	v_mov_b32_e32 v4, v140
	v_mov_b32_e32 v5, v141
	v_mov_b32_e32 v6, v142
	v_mov_b32_e32 v7, v143
	v_lshlrev_b32_e32 v9, 16, v4
	v_and_b32_e32 v4, 0xffff0000, v4
	v_mul_f32_e32 v4, v4, v4
	v_fmac_f32_e32 v4, v9, v9
	v_add_f32_e32 v4, v4, v8
	v_lshlrev_b32_e32 v8, 16, v5
	v_and_b32_e32 v5, 0xffff0000, v5
	v_mul_f32_e32 v5, v5, v5
	v_fmac_f32_e32 v5, v8, v8
	v_add_f32_e32 v4, v5, v4
	v_lshlrev_b32_e32 v5, 16, v6
	v_and_b32_e32 v6, 0xffff0000, v6
	v_mul_f32_e32 v6, v6, v6
	v_fmac_f32_e32 v6, v5, v5
	v_add_f32_e32 v4, v6, v4
	v_and_b32_e32 v6, 0xffff0000, v7
	v_lshlrev_b32_e32 v5, 16, v7
	v_mul_f32_e32 v6, v6, v6
	v_fmac_f32_e32 v6, v5, v5
	v_add_f32_e32 v8, v6, v4
	s_waitcnt vmcnt(4)
	v_mov_b32_e32 v4, v144
	v_mov_b32_e32 v5, v145
	v_mov_b32_e32 v6, v146
	v_mov_b32_e32 v7, v147
	v_lshlrev_b32_e32 v9, 16, v4
	v_and_b32_e32 v4, 0xffff0000, v4
	v_mul_f32_e32 v4, v4, v4
	v_fmac_f32_e32 v4, v9, v9
	v_add_f32_e32 v4, v4, v8
	v_lshlrev_b32_e32 v8, 16, v5
	v_and_b32_e32 v5, 0xffff0000, v5
	v_mul_f32_e32 v5, v5, v5
	v_fmac_f32_e32 v5, v8, v8
	v_add_f32_e32 v4, v5, v4
	v_lshlrev_b32_e32 v5, 16, v6
	v_and_b32_e32 v6, 0xffff0000, v6
	v_mul_f32_e32 v6, v6, v6
	v_fmac_f32_e32 v6, v5, v5
	v_add_f32_e32 v4, v6, v4
	v_and_b32_e32 v6, 0xffff0000, v7
	v_lshlrev_b32_e32 v5, 16, v7
	v_mul_f32_e32 v6, v6, v6
	v_fmac_f32_e32 v6, v5, v5
	v_add_f32_e32 v8, v6, v4
	s_waitcnt vmcnt(3)
	v_mov_b32_e32 v4, v148
	v_mov_b32_e32 v5, v149
	v_mov_b32_e32 v6, v150
	v_mov_b32_e32 v7, v151
	v_lshlrev_b32_e32 v9, 16, v4
	v_and_b32_e32 v4, 0xffff0000, v4
	v_mul_f32_e32 v4, v4, v4
	v_fmac_f32_e32 v4, v9, v9
	v_add_f32_e32 v4, v4, v8
	v_lshlrev_b32_e32 v8, 16, v5
	v_and_b32_e32 v5, 0xffff0000, v5
	v_mul_f32_e32 v5, v5, v5
	v_fmac_f32_e32 v5, v8, v8
	v_add_f32_e32 v4, v5, v4
	v_lshlrev_b32_e32 v5, 16, v6
	v_and_b32_e32 v6, 0xffff0000, v6
	v_mul_f32_e32 v6, v6, v6
	v_fmac_f32_e32 v6, v5, v5
	v_add_f32_e32 v4, v6, v4
	v_and_b32_e32 v6, 0xffff0000, v7
	v_lshlrev_b32_e32 v5, 16, v7
	v_mul_f32_e32 v6, v6, v6
	v_fmac_f32_e32 v6, v5, v5
	v_add_f32_e32 v8, v6, v4
	s_waitcnt vmcnt(2)
	v_mov_b32_e32 v4, v152
	v_mov_b32_e32 v5, v153
	v_mov_b32_e32 v6, v154
	v_mov_b32_e32 v7, v155
	v_lshlrev_b32_e32 v9, 16, v4
	v_and_b32_e32 v4, 0xffff0000, v4
	v_mul_f32_e32 v4, v4, v4
	v_fmac_f32_e32 v4, v9, v9
	v_add_f32_e32 v4, v4, v8
	v_lshlrev_b32_e32 v8, 16, v5
	v_and_b32_e32 v5, 0xffff0000, v5
	v_mul_f32_e32 v5, v5, v5
	v_fmac_f32_e32 v5, v8, v8
	v_add_f32_e32 v8, v5, v4
	v_lshlrev_b32_e32 v5, 16, v7
	v_lshlrev_b32_e32 v4, 16, v6
	v_and_b32_e32 v7, 0xffff0000, v7
	v_and_b32_e32 v6, 0xffff0000, v6
	v_pk_mul_f32 v[6:7], v[6:7], v[6:7]
	s_nop 0
	v_pk_fma_f32 v[4:5], v[4:5], v[4:5], v[6:7]
	s_nop 0
	v_add_f32_e32 v4, v4, v8
	v_add_f32_e32 v10, v5, v4
	s_waitcnt vmcnt(1)
; DI float shx(float v, int m, int lane) { return __builtin_bit_cast(float, __builtin_amdgcn_ds_bpermute((lane ^ m) << 2, __builtin_bit_cast(int, v))); }
; DI void load_q(bf16x8 (&q)[8], const bf16* qrow, int h, const float* gain, int lane) {
;     ...
;     for (int s = 0; s < 8; ++s) { const u32x4 raw = *(const u32x4*)(qrow + 16 * s + 8 * h);
; #pragma unroll
;         for (int j = 0; j < 4; ++j) { const float a = __builtin_bit_cast(float, raw[j] << 16), b = __builtin_bit_cast(float, raw[j] & 0xffff0000u); ss += a * a + b * b; } }
;     ss += shx(ss, 32, lane);
;     const float rs = rsqrtf(ss * (1.0f / HD) + EPS) * C2;
;     asm volatile("" ::: "memory");
; #pragma unroll
;     for (int s = 0; s < 8; ++s) {
;         const u32x4 raw = *(const u32x4*)(qrow + 16 * s + 8 * h);
;         const f32x4 g0 = *(const f32x4*)(gain + 16 * s + 8 * h), g1 = *(const f32x4*)(gain + 16 * s + 8 * h + 4);
;         u32x4 w;
;         w.x = pk2(__builtin_bit_cast(float, raw.x << 16) * rs * g0[0], __builtin_bit_cast(float, raw.x & 0xffff0000u) * rs * g0[1]);
;         w.y = pk2(__builtin_bit_cast(float, raw.y << 16) * rs * g0[2], __builtin_bit_cast(float, raw.y & 0xffff0000u) * rs * g0[3]);
;         w.z = pk2(__builtin_bit_cast(float, raw.z << 16) * rs * g1[0], __builtin_bit_cast(float, raw.z & 0xffff0000u) * rs * g1[1]);
;         w.w = pk2(__builtin_bit_cast(float, raw.w << 16) * rs * g1[2], __builtin_bit_cast(float, raw.w & 0xffff0000u) * rs * g1[3]);
;         q[s] = __builtin_bit_cast(bf16x8, w);
;     }
; DI void fox_unit(const P& p, ldsp lds, int u, int l, int wv) {
;     ...
;     { const float* fq = p.fqn + l * HD; const float* fk = p.fkn + l * HD;
;       float gq = fmaxf(fabsf(fq[lane]), fabsf(fq[lane + 64])), gk = fmaxf(fabsf(fk[lane]), fabsf(fk[lane + 64]));
; #pragma unroll
;       for (int o2 = 1; o2 < 64; o2 <<= 1) { gq = fmaxf(gq, shx(gq, o2, lane)); gk = fmaxf(gk, shx(gk, o2, lane)); }
;       const float BQK = 1.02f * C2 * 128.0f * gq * gk;
;       c.bqk = BQK; c.xsel = false;
;       const float thr = c.cumb[qb * 256] - 2.0f * BQK - 32.0f;
;       const int nt = 4 * qb + 4;
;       const bool skip0 = (lane < nt) && (c.cumb[lane * 64 + 63] < thr);
;       const bool skip1 = (lane + 64 < nt) && (c.cumb[(lane + 64) * 64 + 63] < thr);
;       tstart = __popcll(__ballot(skip0)) + __popcll(__ballot(skip1)); }
	v_mov_b32_e32 v4, v156
	v_mov_b32_e32 v5, v157
	v_mov_b32_e32 v6, v158
	v_mov_b32_e32 v7, v159
	v_lshlrev_b32_e32 v9, 16, v5
	v_lshlrev_b32_e32 v8, 16, v4
	v_and_b32_e32 v5, 0xffff0000, v5
	v_and_b32_e32 v4, 0xffff0000, v4
	v_pk_mul_f32 v[4:5], v[4:5], v[4:5]
	s_nop 0
	v_pk_fma_f32 v[4:5], v[8:9], v[8:9], v[4:5]
	s_nop 0
	v_add_f32_e32 v4, v4, v10
	v_add_f32_e32 v8, v5, v4
	v_lshlrev_b32_e32 v5, 16, v7
	v_lshlrev_b32_e32 v4, 16, v6
	v_and_b32_e32 v7, 0xffff0000, v7
	v_and_b32_e32 v6, 0xffff0000, v6
	v_pk_mul_f32 v[6:7], v[6:7], v[6:7]
	s_nop 0
	v_pk_fma_f32 v[4:5], v[4:5], v[4:5], v[6:7]
	s_nop 0
	v_add_f32_e32 v4, v4, v8
	v_add_f32_e32 v10, v5, v4
	s_waitcnt vmcnt(0)
	v_mov_b32_e32 v4, v160
	v_mov_b32_e32 v5, v161
	v_mov_b32_e32 v6, v162
	v_mov_b32_e32 v7, v163
	global_load_dwordx4 v[136:139], v[2:3], off
	s_waitcnt vmcnt(1)
	v_lshlrev_b32_e32 v9, 16, v5
	v_lshlrev_b32_e32 v8, 16, v4
	v_and_b32_e32 v5, 0xffff0000, v5
	v_and_b32_e32 v4, 0xffff0000, v4
	v_pk_mul_f32 v[4:5], v[4:5], v[4:5]
	s_nop 0
	v_pk_fma_f32 v[4:5], v[8:9], v[8:9], v[4:5]
	s_nop 0
	v_add_f32_e32 v4, v4, v10
	v_add_f32_e32 v8, v5, v4
	v_lshlrev_b32_e32 v5, 16, v7
	v_lshlrev_b32_e32 v4, 16, v6
	v_and_b32_e32 v7, 0xffff0000, v7
	v_and_b32_e32 v6, 0xffff0000, v6
	v_pk_mul_f32 v[6:7], v[6:7], v[6:7]
	v_and_b32_e32 v10, 32, v114
	v_pk_fma_f32 v[4:5], v[4:5], v[4:5], v[6:7]
	s_nop 0
	v_add_f32_e32 v4, v4, v8
	v_add_f32_e32 v201, v5, v4
	global_load_dwordx4 v[180:183], v10, s[8:9] offset:16
	global_load_dwordx4 v[184:187], v10, s[8:9]
	global_load_dwordx4 v[140:143], v[2:3], off offset:32
	global_load_dwordx4 v[172:175], v10, s[8:9] offset:80
	global_load_dwordx4 v[176:179], v10, s[8:9] offset:64
	global_load_dwordx4 v[144:147], v[2:3], off offset:64
	global_load_dwordx4 v[164:167], v10, s[8:9] offset:144
	global_load_dwordx4 v[168:171], v10, s[8:9] offset:128
	global_load_dwordx4 v[148:151], v[2:3], off offset:96
	global_load_dwordx4 v[156:159], v10, s[8:9] offset:208
	global_load_dwordx4 v[160:163], v10, s[8:9] offset:192
	global_load_dwordx4 v[110:113], v[2:3], off offset:128
	global_load_dwordx4 v[106:109], v10, s[8:9] offset:272
	global_load_dwordx4 v[152:155], v10, s[8:9] offset:256
	global_load_dwordx4 v[98:101], v[2:3], off offset:160
	global_load_dwordx4 v[94:97], v10, s[8:9] offset:336
	global_load_dwordx4 v[102:105], v10, s[8:9] offset:320
	global_load_dwordx4 v[86:89], v[2:3], off offset:192
	global_load_dwordx4 v[82:85], v10, s[8:9] offset:400
	global_load_dwordx4 v[90:93], v10, s[8:9] offset:384
	global_load_dwordx4 v[6:9], v[2:3], off offset:224
	s_nop 0
	global_load_dwordx4 v[2:5], v10, s[8:9] offset:464
	s_nop 0
	global_load_dwordx4 v[10:13], v10, s[8:9] offset:448
	s_nop 0
	global_load_dword v15, v14, s[8:9]
	global_load_dword v16, v14, s[8:9] offset:256
	v_readlane_b32 s8, v255, 11
	v_readlane_b32 s9, v255, 12
	ds_bpermute_b32 v210, v197, v201
	s_waitcnt vmcnt(1)
	v_max_f32_e64 v15, |v15|, |v15|
	s_waitcnt vmcnt(0)
	v_max_f32_e64 v16, |v16|, |v16|
	v_max_f32_e32 v15, v15, v16
	global_load_dword v16, v14, s[8:9]
	global_load_dword v17, v14, s[8:9] offset:256
	s_lshl_b64 s[8:9], s[4:5], 2
	s_add_u32 s8, s2, s8
	s_addc_u32 s9, s3, s9
	s_lshl_b32 s5, s6, 2
	s_add_i32 s15, s5, 4
	v_cmp_gt_u32_e32 vcc, s15, v208
	s_waitcnt vmcnt(1)
	v_max_f32_e64 v16, |v16|, |v16|
	s_waitcnt vmcnt(0)
	v_max_f32_e64 v17, |v17|, |v17|
	v_max_f32_e32 v16, v16, v17
	v_xor_b32_e32 v17, 4, v14
	ds_bpermute_b32 v18, v17, v15
	ds_bpermute_b32 v17, v17, v16
	s_waitcnt lgkmcnt(1)
	v_max_f32_e32 v18, v18, v18
	s_waitcnt lgkmcnt(0)
	v_max_f32_e32 v17, v17, v17
	v_max_f32_e32 v15, v15, v18
	v_max_f32_e32 v16, v16, v17
	v_xor_b32_e32 v17, 8, v14
	ds_bpermute_b32 v18, v17, v15
	ds_bpermute_b32 v17, v17, v16
	s_waitcnt lgkmcnt(1)
	v_max_f32_e32 v18, v18, v18
	s_waitcnt lgkmcnt(0)
	v_max_f32_e32 v17, v17, v17
	v_max_f32_e32 v15, v15, v18
	v_max_f32_e32 v16, v16, v17
	v_xor_b32_e32 v17, 16, v14
	ds_bpermute_b32 v18, v17, v15
	ds_bpermute_b32 v17, v17, v16
	s_waitcnt lgkmcnt(1)
	v_max_f32_e32 v18, v18, v18
	s_waitcnt lgkmcnt(0)
	v_max_f32_e32 v17, v17, v17
	v_max_f32_e32 v15, v15, v18
	v_max_f32_e32 v16, v16, v17
	v_xor_b32_e32 v17, 32, v14
	ds_bpermute_b32 v18, v17, v15
	ds_bpermute_b32 v17, v17, v16
	v_xor_b32_e32 v14, 64, v14
	s_waitcnt lgkmcnt(1)
	v_max_f32_e32 v18, v18, v18
	v_max_f32_e32 v15, v15, v18
	s_waitcnt lgkmcnt(0)
	v_max_f32_e32 v17, v17, v17
	v_max_f32_e32 v16, v16, v17
	ds_bpermute_b32 v17, v14, v15
	ds_bpermute_b32 v14, v14, v16
	s_waitcnt lgkmcnt(1)
	v_max_f32_e32 v17, v17, v17
	v_max_f32_e32 v15, v15, v17
	s_waitcnt lgkmcnt(0)
	v_max_f32_e32 v14, v14, v14
	v_max_f32_e32 v14, v16, v14
	ds_bpermute_b32 v16, v197, v15
	s_waitcnt lgkmcnt(0)
	v_max_f32_e32 v16, v16, v16
	v_max_f32_e32 v15, v15, v16
	ds_bpermute_b32 v16, v197, v14
	v_mul_f32_e32 v15, 0x4185307d, v15
	s_waitcnt lgkmcnt(0)
	v_max_f32_e32 v16, v16, v16
	v_max_f32_e32 v14, v14, v16
	v_mul_f32_e32 v190, v14, v15
	global_load_dword v14, v1, s[8:9]
	v_lshlrev_b32_e32 v15, 8, v208
	global_load_dword v16, v15, s[2:3] offset:252
	v_or_b32_e32 v17, 64, v208
	v_lshlrev_b32_e32 v17, 8, v17
	global_load_dword v17, v17, s[2:3] offset:252
	s_mov_b64 s[8:9], 0
	s_waitcnt vmcnt(0)
	v_fmac_f32_e32 v14, -2.0, v190
	v_add_f32_e32 v14, 0xc2000000, v14
	s_and_saveexec_b64 s[12:13], vcc
	s_cbranch_execz .LBB0_526
	v_cmp_lt_f32_e32 vcc, v16, v14
	s_and_b64 s[10:11], vcc, exec
.LBB0_526:
	s_or_b64 exec, exec, s[12:13]
	v_or_b32_e32 v15, 64, v208
	v_cmp_gt_u32_e32 vcc, s15, v15
	s_and_saveexec_b64 s[12:13], vcc
	s_cbranch_execz .LBB0_528
	v_cmp_lt_f32_e32 vcc, v17, v14
	s_and_b64 s[8:9], vcc, exec
